# post-solve section: one address base plus immediate offsets, single conditional region for the second block, packed bf16 pair conversion with d16_hi writes
# speedup vs baseline: 1.0183x; 1.0015x over previous
.LBB0_216:
	s_and_b64 vcc, exec, s[28:29]
	s_cbranch_vccz .LBB0_236
	s_setprio 2
	v_lshlrev_b32_e32 v3, 2, v1
	v_ashrrev_i32_e32 v33, 7, v1
	s_movk_i32 s6, 0x2080
	v_and_b32_e32 v32, 12, v3
	v_ashrrev_i32_e32 v14, 2, v1
	v_mul_lo_u32 v2, v33, s6
	v_lshlrev_b32_e32 v19, 2, v32
	v_readlane_b32 s6, v253, 51
	v_and_b32_e32 v15, 31, v14
	v_cmp_eq_u32_e32 vcc, v32, v15
	v_add3_u32 v6, s6, v2, v19
	ds_read_b128 v[150:153], v6
	ds_read_b128 v[154:157], v6 offset:64
	ds_read_b128 v[158:161], v6 offset:256
	ds_read_b128 v[162:165], v6 offset:320
	ds_read_b128 v[166:169], v6 offset:512
	ds_read_b128 v[170:173], v6 offset:576
	ds_read_b128 v[174:177], v6 offset:768
	ds_read_b128 v[178:181], v6 offset:832
	ds_read_b128 v[182:185], v6 offset:1024
	ds_read_b128 v[186:189], v6 offset:1088
	ds_read_b128 v[190:193], v6 offset:1280
	ds_read_b128 v[194:197], v6 offset:1344
	v_cndmask_b32_e64 v12, 0, 1.0, vcc
	v_or_b32_e32 v31, 1, v32
	v_cmp_eq_u32_e32 vcc, v31, v15
	v_or_b32_e32 v30, 2, v32
	s_nop 0
	v_cndmask_b32_e64 v13, 0, 1.0, vcc
	v_cmp_eq_u32_e32 vcc, v30, v15
	v_or_b32_e32 v29, 3, v32
	v_or_b32_e32 v28, 16, v32
	v_cndmask_b32_e64 v16, 0, 1.0, vcc
	v_cmp_eq_u32_e32 vcc, v29, v15
	s_waitcnt vmcnt(1)
	s_nop 0
	v_cndmask_b32_e64 v17, 0, 1.0, vcc
	v_cmp_eq_u32_e32 vcc, v28, v15
	v_or_b32_e32 v27, 17, v32
	v_or_b32_e32 v26, 18, v32
	v_cndmask_b32_e64 v22, 0, 1.0, vcc
	v_cmp_eq_u32_e32 vcc, v27, v15
	s_nop 1
	v_cndmask_b32_e64 v23, 0, 1.0, vcc
	v_cmp_eq_u32_e32 vcc, v26, v15
	v_or_b32_e32 v21, 19, v32
	s_nop 0
	v_cndmask_b32_e64 v114, 0, 1.0, vcc
	v_cmp_eq_u32_e32 vcc, v21, v15
	v_mov_b32_dpp v18, v12 quad_perm:[0,0,0,0] row_mask:0xf bank_mask:0xf
	s_nop 0
	v_cndmask_b32_e64 v115, 0, 1.0, vcc
	s_waitcnt lgkmcnt(11)
	v_pk_fma_f32 v[12:13], v[150:151], v[18:19], v[12:13] op_sel_hi:[1,0,1] neg_lo:[0,1,0] neg_hi:[0,1,0]
	v_pk_fma_f32 v[16:17], v[152:153], v[18:19], v[16:17] op_sel_hi:[1,0,1] neg_lo:[0,1,0] neg_hi:[0,1,0]
	ds_read_b128 v[150:153], v6 offset:1536
	s_waitcnt lgkmcnt(11)
	v_pk_fma_f32 v[22:23], v[154:155], v[18:19], v[22:23] op_sel_hi:[1,0,1] neg_lo:[0,1,0] neg_hi:[0,1,0]
	v_pk_fma_f32 v[114:115], v[156:157], v[18:19], v[114:115] op_sel_hi:[1,0,1] neg_lo:[0,1,0] neg_hi:[0,1,0]
	ds_read_b128 v[154:157], v6 offset:1600
	v_mov_b32_e32 v20, v131
	v_readlane_b32 s6, v253, 52
	v_mov_b32_dpp v18, v13 quad_perm:[0,0,0,0] row_mask:0xf bank_mask:0xf
	s_waitcnt lgkmcnt(11)
	v_pk_fma_f32 v[16:17], v[160:161], v[18:19], v[16:17] op_sel_hi:[1,0,1] neg_lo:[0,1,0] neg_hi:[0,1,0]
	v_pk_fma_f32 v[12:13], v[158:159], v[18:19], v[12:13] op_sel_hi:[1,0,1] neg_lo:[0,1,0] neg_hi:[0,1,0]
	ds_read_b128 v[158:161], v6 offset:1792
	s_waitcnt lgkmcnt(11)
	v_pk_fma_f32 v[114:115], v[164:165], v[18:19], v[114:115] op_sel_hi:[1,0,1] neg_lo:[0,1,0] neg_hi:[0,1,0]
	v_pk_fma_f32 v[22:23], v[162:163], v[18:19], v[22:23] op_sel_hi:[1,0,1] neg_lo:[0,1,0] neg_hi:[0,1,0]
	ds_read_b128 v[162:165], v6 offset:1856
	s_movk_i32 s8, 0x48
	v_cmp_eq_u32_e32 vcc, 1, v33
	v_mov_b32_dpp v18, v16 quad_perm:[0,0,0,0] row_mask:0xf bank_mask:0xf
	s_waitcnt lgkmcnt(11)
	v_pk_fma_f32 v[16:17], v[168:169], v[18:19], v[16:17] op_sel_hi:[1,0,1] neg_lo:[0,1,0] neg_hi:[0,1,0]
	v_pk_fma_f32 v[12:13], v[166:167], v[18:19], v[12:13] op_sel_hi:[1,0,1] neg_lo:[0,1,0] neg_hi:[0,1,0]
	ds_read_b128 v[166:169], v6 offset:2048
	s_waitcnt lgkmcnt(11)
	v_pk_fma_f32 v[114:115], v[172:173], v[18:19], v[114:115] op_sel_hi:[1,0,1] neg_lo:[0,1,0] neg_hi:[0,1,0]
	v_pk_fma_f32 v[22:23], v[170:171], v[18:19], v[22:23] op_sel_hi:[1,0,1] neg_lo:[0,1,0] neg_hi:[0,1,0]
	ds_read_b128 v[170:173], v6 offset:2112
	v_mov_b32_dpp v18, v17 quad_perm:[0,0,0,0] row_mask:0xf bank_mask:0xf
	s_waitcnt lgkmcnt(11)
	v_pk_fma_f32 v[12:13], v[174:175], v[18:19], v[12:13] op_sel_hi:[1,0,1] neg_lo:[0,1,0] neg_hi:[0,1,0]
	v_pk_fma_f32 v[16:17], v[176:177], v[18:19], v[16:17] op_sel_hi:[1,0,1] neg_lo:[0,1,0] neg_hi:[0,1,0]
	ds_read_b128 v[174:177], v6 offset:2304
	s_waitcnt lgkmcnt(11)
	v_pk_fma_f32 v[114:115], v[180:181], v[18:19], v[114:115] op_sel_hi:[1,0,1] neg_lo:[0,1,0] neg_hi:[0,1,0]
	v_pk_fma_f32 v[22:23], v[178:179], v[18:19], v[22:23] op_sel_hi:[1,0,1] neg_lo:[0,1,0] neg_hi:[0,1,0]
	ds_read_b128 v[178:181], v6 offset:2368
	v_mov_b32_dpp v18, v12 quad_perm:[1,1,1,1] row_mask:0xf bank_mask:0xf
	s_waitcnt lgkmcnt(11)
	v_pk_fma_f32 v[12:13], v[182:183], v[18:19], v[12:13] op_sel_hi:[1,0,1] neg_lo:[0,1,0] neg_hi:[0,1,0]
	v_pk_fma_f32 v[16:17], v[184:185], v[18:19], v[16:17] op_sel_hi:[1,0,1] neg_lo:[0,1,0] neg_hi:[0,1,0]
	ds_read_b128 v[182:185], v6 offset:2560
	s_waitcnt lgkmcnt(11)
	v_pk_fma_f32 v[22:23], v[186:187], v[18:19], v[22:23] op_sel_hi:[1,0,1] neg_lo:[0,1,0] neg_hi:[0,1,0]
	v_pk_fma_f32 v[114:115], v[188:189], v[18:19], v[114:115] op_sel_hi:[1,0,1] neg_lo:[0,1,0] neg_hi:[0,1,0]
	ds_read_b128 v[186:189], v6 offset:2624
	v_mov_b32_dpp v18, v13 quad_perm:[1,1,1,1] row_mask:0xf bank_mask:0xf
	s_waitcnt lgkmcnt(11)
	v_pk_fma_f32 v[16:17], v[192:193], v[18:19], v[16:17] op_sel_hi:[1,0,1] neg_lo:[0,1,0] neg_hi:[0,1,0]
	v_pk_fma_f32 v[12:13], v[190:191], v[18:19], v[12:13] op_sel_hi:[1,0,1] neg_lo:[0,1,0] neg_hi:[0,1,0]
	ds_read_b128 v[190:193], v6 offset:2816
	s_waitcnt lgkmcnt(11)
	v_pk_fma_f32 v[114:115], v[196:197], v[18:19], v[114:115] op_sel_hi:[1,0,1] neg_lo:[0,1,0] neg_hi:[0,1,0]
	v_pk_fma_f32 v[22:23], v[194:195], v[18:19], v[22:23] op_sel_hi:[1,0,1] neg_lo:[0,1,0] neg_hi:[0,1,0]
	ds_read_b128 v[194:197], v6 offset:2880
	v_mov_b32_dpp v18, v16 quad_perm:[1,1,1,1] row_mask:0xf bank_mask:0xf
	s_waitcnt lgkmcnt(11)
	v_pk_fma_f32 v[16:17], v[152:153], v[18:19], v[16:17] op_sel_hi:[1,0,1] neg_lo:[0,1,0] neg_hi:[0,1,0]
	v_pk_fma_f32 v[12:13], v[150:151], v[18:19], v[12:13] op_sel_hi:[1,0,1] neg_lo:[0,1,0] neg_hi:[0,1,0]
	ds_read_b128 v[150:153], v6 offset:3072
	s_waitcnt lgkmcnt(11)
	v_pk_fma_f32 v[22:23], v[154:155], v[18:19], v[22:23] op_sel_hi:[1,0,1] neg_lo:[0,1,0] neg_hi:[0,1,0]
	v_pk_fma_f32 v[114:115], v[156:157], v[18:19], v[114:115] op_sel_hi:[1,0,1] neg_lo:[0,1,0] neg_hi:[0,1,0]
	ds_read_b128 v[154:157], v6 offset:3136
	v_mov_b32_dpp v18, v17 quad_perm:[1,1,1,1] row_mask:0xf bank_mask:0xf
	s_waitcnt lgkmcnt(11)
	v_pk_fma_f32 v[12:13], v[158:159], v[18:19], v[12:13] op_sel_hi:[1,0,1] neg_lo:[0,1,0] neg_hi:[0,1,0]
	v_pk_fma_f32 v[16:17], v[160:161], v[18:19], v[16:17] op_sel_hi:[1,0,1] neg_lo:[0,1,0] neg_hi:[0,1,0]
	ds_read_b128 v[158:161], v6 offset:3328
	s_waitcnt lgkmcnt(11)
	v_pk_fma_f32 v[114:115], v[164:165], v[18:19], v[114:115] op_sel_hi:[1,0,1] neg_lo:[0,1,0] neg_hi:[0,1,0]
	v_pk_fma_f32 v[22:23], v[162:163], v[18:19], v[22:23] op_sel_hi:[1,0,1] neg_lo:[0,1,0] neg_hi:[0,1,0]
	ds_read_b128 v[162:165], v6 offset:3392
	v_mov_b32_dpp v18, v12 quad_perm:[2,2,2,2] row_mask:0xf bank_mask:0xf
	s_waitcnt lgkmcnt(11)
	v_pk_fma_f32 v[12:13], v[166:167], v[18:19], v[12:13] op_sel_hi:[1,0,1] neg_lo:[0,1,0] neg_hi:[0,1,0]
	v_pk_fma_f32 v[16:17], v[168:169], v[18:19], v[16:17] op_sel_hi:[1,0,1] neg_lo:[0,1,0] neg_hi:[0,1,0]
	ds_read_b128 v[166:169], v6 offset:3584
	s_waitcnt lgkmcnt(11)
	v_pk_fma_f32 v[22:23], v[170:171], v[18:19], v[22:23] op_sel_hi:[1,0,1] neg_lo:[0,1,0] neg_hi:[0,1,0]
	v_pk_fma_f32 v[114:115], v[172:173], v[18:19], v[114:115] op_sel_hi:[1,0,1] neg_lo:[0,1,0] neg_hi:[0,1,0]
	ds_read_b128 v[170:173], v6 offset:3648
	v_mov_b32_dpp v18, v13 quad_perm:[2,2,2,2] row_mask:0xf bank_mask:0xf
	s_waitcnt lgkmcnt(11)
	v_pk_fma_f32 v[16:17], v[176:177], v[18:19], v[16:17] op_sel_hi:[1,0,1] neg_lo:[0,1,0] neg_hi:[0,1,0]
	v_pk_fma_f32 v[12:13], v[174:175], v[18:19], v[12:13] op_sel_hi:[1,0,1] neg_lo:[0,1,0] neg_hi:[0,1,0]
	ds_read_b128 v[174:177], v6 offset:3840
	s_waitcnt lgkmcnt(11)
	v_pk_fma_f32 v[114:115], v[180:181], v[18:19], v[114:115] op_sel_hi:[1,0,1] neg_lo:[0,1,0] neg_hi:[0,1,0]
	v_pk_fma_f32 v[22:23], v[178:179], v[18:19], v[22:23] op_sel_hi:[1,0,1] neg_lo:[0,1,0] neg_hi:[0,1,0]
	ds_read_b128 v[178:181], v6 offset:3904
	v_mov_b32_dpp v18, v16 quad_perm:[2,2,2,2] row_mask:0xf bank_mask:0xf
	s_waitcnt lgkmcnt(11)
	v_pk_fma_f32 v[16:17], v[184:185], v[18:19], v[16:17] op_sel_hi:[1,0,1] neg_lo:[0,1,0] neg_hi:[0,1,0]
	v_pk_fma_f32 v[12:13], v[182:183], v[18:19], v[12:13] op_sel_hi:[1,0,1] neg_lo:[0,1,0] neg_hi:[0,1,0]
	ds_read_b128 v[182:185], v6 offset:4160
	s_waitcnt lgkmcnt(11)
	v_pk_fma_f32 v[22:23], v[186:187], v[18:19], v[22:23] op_sel_hi:[1,0,1] neg_lo:[0,1,0] neg_hi:[0,1,0]
	v_pk_fma_f32 v[114:115], v[188:189], v[18:19], v[114:115] op_sel_hi:[1,0,1] neg_lo:[0,1,0] neg_hi:[0,1,0]
	ds_read_b128 v[186:189], v6 offset:4416
	v_mov_b32_dpp v18, v17 quad_perm:[2,2,2,2] row_mask:0xf bank_mask:0xf
	s_waitcnt lgkmcnt(11)
	v_pk_fma_f32 v[12:13], v[190:191], v[18:19], v[12:13] op_sel_hi:[1,0,1] neg_lo:[0,1,0] neg_hi:[0,1,0]
	v_pk_fma_f32 v[16:17], v[192:193], v[18:19], v[16:17] op_sel_hi:[1,0,1] neg_lo:[0,1,0] neg_hi:[0,1,0]
	ds_read_b128 v[190:193], v6 offset:4672
	s_waitcnt lgkmcnt(11)
	v_pk_fma_f32 v[114:115], v[196:197], v[18:19], v[114:115] op_sel_hi:[1,0,1] neg_lo:[0,1,0] neg_hi:[0,1,0]
	v_pk_fma_f32 v[22:23], v[194:195], v[18:19], v[22:23] op_sel_hi:[1,0,1] neg_lo:[0,1,0] neg_hi:[0,1,0]
	ds_read_b128 v[194:197], v6 offset:4928
	v_mov_b32_dpp v18, v12 quad_perm:[3,3,3,3] row_mask:0xf bank_mask:0xf
	s_waitcnt lgkmcnt(11)
	v_pk_fma_f32 v[12:13], v[150:151], v[18:19], v[12:13] op_sel_hi:[1,0,1] neg_lo:[0,1,0] neg_hi:[0,1,0]
	v_pk_fma_f32 v[16:17], v[152:153], v[18:19], v[16:17] op_sel_hi:[1,0,1] neg_lo:[0,1,0] neg_hi:[0,1,0]
	ds_read_b128 v[150:153], v6 offset:5184
	s_waitcnt lgkmcnt(11)
	v_pk_fma_f32 v[22:23], v[154:155], v[18:19], v[22:23] op_sel_hi:[1,0,1] neg_lo:[0,1,0] neg_hi:[0,1,0]
	v_pk_fma_f32 v[114:115], v[156:157], v[18:19], v[114:115] op_sel_hi:[1,0,1] neg_lo:[0,1,0] neg_hi:[0,1,0]
	ds_read_b128 v[154:157], v6 offset:5440
	v_mov_b32_dpp v18, v13 quad_perm:[3,3,3,3] row_mask:0xf bank_mask:0xf
	s_waitcnt lgkmcnt(11)
	v_pk_fma_f32 v[16:17], v[160:161], v[18:19], v[16:17] op_sel_hi:[1,0,1] neg_lo:[0,1,0] neg_hi:[0,1,0]
	v_pk_fma_f32 v[12:13], v[158:159], v[18:19], v[12:13] op_sel_hi:[1,0,1] neg_lo:[0,1,0] neg_hi:[0,1,0]
	ds_read_b128 v[158:161], v6 offset:5696
	s_waitcnt lgkmcnt(11)
	v_pk_fma_f32 v[104:105], v[164:165], v[18:19], v[114:115] op_sel_hi:[1,0,1] neg_lo:[0,1,0] neg_hi:[0,1,0]
	v_pk_fma_f32 v[22:23], v[162:163], v[18:19], v[22:23] op_sel_hi:[1,0,1] neg_lo:[0,1,0] neg_hi:[0,1,0]
	ds_read_b128 v[162:165], v6 offset:5952
	v_mov_b32_dpp v18, v16 quad_perm:[3,3,3,3] row_mask:0xf bank_mask:0xf
	s_waitcnt lgkmcnt(11)
	v_pk_fma_f32 v[16:17], v[168:169], v[18:19], v[16:17] op_sel_hi:[1,0,1] neg_lo:[0,1,0] neg_hi:[0,1,0]
	v_pk_fma_f32 v[114:115], v[166:167], v[18:19], v[12:13] op_sel_hi:[1,0,1] neg_lo:[0,1,0] neg_hi:[0,1,0]
	ds_read_b128 v[166:169], v6 offset:6208
	s_waitcnt lgkmcnt(11)
	v_pk_fma_f32 v[12:13], v[170:171], v[18:19], v[22:23] op_sel_hi:[1,0,1] neg_lo:[0,1,0] neg_hi:[0,1,0]
	v_pk_fma_f32 v[22:23], v[172:173], v[18:19], v[104:105] op_sel_hi:[1,0,1] neg_lo:[0,1,0] neg_hi:[0,1,0]
	ds_read_b128 v[170:173], v6 offset:6464
	v_mov_b32_dpp v18, v17 quad_perm:[3,3,3,3] row_mask:0xf bank_mask:0xf
	s_waitcnt lgkmcnt(10)
	v_pk_fma_f32 v[12:13], v[178:179], v[18:19], v[12:13] op_sel_hi:[1,0,1] neg_lo:[0,1,0] neg_hi:[0,1,0]
	v_pk_fma_f32 v[22:23], v[180:181], v[18:19], v[22:23] op_sel_hi:[1,0,1] neg_lo:[0,1,0] neg_hi:[0,1,0]
	ds_read_b128 v[178:181], v6 offset:6720
	v_mov_b32_e32 v7, v12
	v_pk_fma_f32 v[2:3], v[174:175], v[18:19], v[114:115] op_sel_hi:[1,0,1] neg_lo:[0,1,0] neg_hi:[0,1,0]
	s_nop 0
	v_mov_b32_dpp v20, v7 quad_perm:[0,0,0,0] row_mask:0xf bank_mask:0xf
	s_waitcnt lgkmcnt(10)
	v_pk_fma_f32 v[12:13], v[182:183], v[20:21], v[12:13] op_sel_hi:[1,0,1] neg_lo:[0,1,0] neg_hi:[0,1,0]
	v_pk_fma_f32 v[22:23], v[184:185], v[20:21], v[22:23] op_sel_hi:[1,0,1] neg_lo:[0,1,0] neg_hi:[0,1,0]
	ds_read_b128 v[182:185], v6 offset:6976
	v_mov_b32_dpp v20, v13 quad_perm:[0,0,0,0] row_mask:0xf bank_mask:0xf
	s_waitcnt lgkmcnt(10)
	v_pk_fma_f32 v[22:23], v[188:189], v[20:21], v[22:23] op_sel_hi:[1,0,1] neg_lo:[0,1,0] neg_hi:[0,1,0]
	v_pk_fma_f32 v[12:13], v[186:187], v[20:21], v[12:13] op_sel_hi:[1,0,1] neg_lo:[0,1,0] neg_hi:[0,1,0]
	ds_read_b128 v[186:189], v6 offset:7232
	v_mov_b32_e32 v20, v131
	v_mov_b32_e32 v7, v22
	s_nop 1
	v_mov_b32_dpp v20, v7 quad_perm:[0,0,0,0] row_mask:0xf bank_mask:0xf
	s_waitcnt lgkmcnt(10)
	v_pk_fma_f32 v[22:23], v[192:193], v[20:21], v[22:23] op_sel_hi:[1,0,1] neg_lo:[0,1,0] neg_hi:[0,1,0]
	v_pk_fma_f32 v[12:13], v[190:191], v[20:21], v[12:13] op_sel_hi:[1,0,1] neg_lo:[0,1,0] neg_hi:[0,1,0]
	ds_read_b128 v[190:193], v6 offset:7488
	v_mov_b32_e32 v20, v131
	v_mov_b32_e32 v7, v23
	s_nop 1
	v_mov_b32_dpp v20, v7 quad_perm:[0,0,0,0] row_mask:0xf bank_mask:0xf
	s_waitcnt lgkmcnt(10)
	v_pk_fma_f32 v[12:13], v[194:195], v[20:21], v[12:13] op_sel_hi:[1,0,1] neg_lo:[0,1,0] neg_hi:[0,1,0]
	v_pk_fma_f32 v[22:23], v[196:197], v[20:21], v[22:23] op_sel_hi:[1,0,1] neg_lo:[0,1,0] neg_hi:[0,1,0]
	ds_read_b128 v[194:197], v6 offset:7744
	v_mov_b32_dpp v20, v12 quad_perm:[1,1,1,1] row_mask:0xf bank_mask:0xf
	s_waitcnt lgkmcnt(10)
	v_pk_fma_f32 v[12:13], v[150:151], v[20:21], v[12:13] op_sel_hi:[1,0,1] neg_lo:[0,1,0] neg_hi:[0,1,0]
	v_pk_fma_f32 v[22:23], v[152:153], v[20:21], v[22:23] op_sel_hi:[1,0,1] neg_lo:[0,1,0] neg_hi:[0,1,0]
	s_nop 0
	v_mov_b32_dpp v20, v13 quad_perm:[1,1,1,1] row_mask:0xf bank_mask:0xf
	s_waitcnt lgkmcnt(9)
	v_pk_fma_f32 v[22:23], v[156:157], v[20:21], v[22:23] op_sel_hi:[1,0,1] neg_lo:[0,1,0] neg_hi:[0,1,0]
	v_pk_fma_f32 v[12:13], v[154:155], v[20:21], v[12:13] op_sel_hi:[1,0,1] neg_lo:[0,1,0] neg_hi:[0,1,0]
	v_mov_b32_e32 v20, v131
	v_mov_b32_e32 v7, v22
	s_nop 1
	v_mov_b32_dpp v20, v7 quad_perm:[1,1,1,1] row_mask:0xf bank_mask:0xf
	s_waitcnt lgkmcnt(8)
	v_pk_fma_f32 v[22:23], v[160:161], v[20:21], v[22:23] op_sel_hi:[1,0,1] neg_lo:[0,1,0] neg_hi:[0,1,0]
	v_pk_fma_f32 v[12:13], v[158:159], v[20:21], v[12:13] op_sel_hi:[1,0,1] neg_lo:[0,1,0] neg_hi:[0,1,0]
	v_mov_b32_e32 v20, v131
	v_mov_b32_e32 v7, v23
	s_nop 1
	v_mov_b32_dpp v20, v7 quad_perm:[1,1,1,1] row_mask:0xf bank_mask:0xf
	s_waitcnt lgkmcnt(7)
	v_pk_fma_f32 v[12:13], v[162:163], v[20:21], v[12:13] op_sel_hi:[1,0,1] neg_lo:[0,1,0] neg_hi:[0,1,0]
	v_pk_fma_f32 v[22:23], v[164:165], v[20:21], v[22:23] op_sel_hi:[1,0,1] neg_lo:[0,1,0] neg_hi:[0,1,0]
	s_nop 0
	v_mov_b32_dpp v20, v12 quad_perm:[2,2,2,2] row_mask:0xf bank_mask:0xf
	s_waitcnt lgkmcnt(6)
	v_pk_fma_f32 v[8:9], v[166:167], v[20:21], v[12:13] op_sel_hi:[1,0,1] neg_lo:[0,1,0] neg_hi:[0,1,0]
	v_mov_b32_e32 v12, v131
	v_mov_b32_e32 v7, v9
	v_pk_fma_f32 v[10:11], v[168:169], v[20:21], v[22:23] op_sel_hi:[1,0,1] neg_lo:[0,1,0] neg_hi:[0,1,0]
	v_mov_b32_e32 v20, v131
	v_mov_b32_dpp v12, v7 quad_perm:[2,2,2,2] row_mask:0xf bank_mask:0xf
	s_waitcnt lgkmcnt(5)
	v_pk_fma_f32 v[10:11], v[172:173], v[12:13], v[10:11] op_sel_hi:[1,0,1] neg_lo:[0,1,0] neg_hi:[0,1,0]
	v_pk_fma_f32 v[8:9], v[170:171], v[12:13], v[8:9] op_sel_hi:[1,0,1] neg_lo:[0,1,0] neg_hi:[0,1,0]
	v_mov_b32_e32 v12, v131
	v_mov_b32_e32 v7, v10
	s_nop 1
	v_mov_b32_dpp v12, v7 quad_perm:[2,2,2,2] row_mask:0xf bank_mask:0xf
	s_waitcnt lgkmcnt(4)
	v_pk_fma_f32 v[22:23], v[180:181], v[12:13], v[10:11] op_sel_hi:[1,0,1] neg_lo:[0,1,0] neg_hi:[0,1,0]
	v_pk_fma_f32 v[8:9], v[178:179], v[12:13], v[8:9] op_sel_hi:[1,0,1] neg_lo:[0,1,0] neg_hi:[0,1,0]
	v_mov_b32_e32 v7, v23
	s_nop 1
	v_mov_b32_dpp v20, v7 quad_perm:[2,2,2,2] row_mask:0xf bank_mask:0xf
	s_waitcnt lgkmcnt(3)
	v_pk_fma_f32 v[102:103], v[182:183], v[20:21], v[8:9] op_sel_hi:[1,0,1] neg_lo:[0,1,0] neg_hi:[0,1,0]
	v_pk_fma_f32 v[22:23], v[184:185], v[20:21], v[22:23] op_sel_hi:[1,0,1] neg_lo:[0,1,0] neg_hi:[0,1,0]
	s_nop 0
	v_mov_b32_dpp v20, v102 quad_perm:[3,3,3,3] row_mask:0xf bank_mask:0xf
	s_waitcnt lgkmcnt(2)
	v_pk_fma_f32 v[100:101], v[188:189], v[20:21], v[22:23] op_sel_hi:[1,0,1] neg_lo:[0,1,0] neg_hi:[0,1,0]
	v_pk_fma_f32 v[22:23], v[186:187], v[20:21], v[102:103] op_sel_hi:[1,0,1] neg_lo:[0,1,0] neg_hi:[0,1,0]
	v_mov_b32_e32 v24, v131
	v_mov_b32_e32 v20, v23
	v_lshlrev_b32_e32 v98, 5, v33
	v_lshl_add_u32 v33, v15, 2, s6
	v_mov_b32_dpp v24, v20 quad_perm:[3,3,3,3] row_mask:0xf bank_mask:0xf
	v_and_b32_e32 v20, -4, v1
	s_waitcnt lgkmcnt(1)
	v_pk_fma_f32 v[12:13], v[192:193], v[24:25], v[100:101] op_sel_hi:[1,0,1] neg_lo:[0,1,0] neg_hi:[0,1,0]
	v_add_u32_e32 v20, 0, v20
	v_mov_b32_e32 v93, v12
	s_waitcnt vmcnt(0)
	v_add_u32_e32 v97, 0x24a00, v20
	v_add_u32_e32 v20, 0x24b00, v20
	ds_read_b32 v97, v97
	ds_read_b32 v99, v20
	v_mov_b32_e32 v20, 0
	v_pk_fma_f32 v[4:5], v[176:177], v[18:19], v[16:17] op_sel_hi:[1,0,1] neg_lo:[0,1,0] neg_hi:[0,1,0]
	v_pk_fma_f32 v[10:11], v[190:191], v[24:25], v[22:23] op_sel_hi:[1,0,1] neg_lo:[0,1,0] neg_hi:[0,1,0]
	v_mov_b32_dpp v20, v93 quad_perm:[3,3,3,3] row_mask:0xf bank_mask:0xf
	v_or_b32_e32 v100, v32, v98
	v_mul_u32_u24_e32 v100, 0x48, v100
	v_pk_fma_f32 v[8:9], v[196:197], v[20:21], v[12:13] op_sel_hi:[1,0,1] neg_lo:[0,1,0] neg_hi:[0,1,0]
	v_pk_fma_f32 v[6:7], v[194:195], v[20:21], v[10:11] op_sel_hi:[1,0,1] neg_lo:[0,1,0] neg_hi:[0,1,0]
	v_add_lshl_u32 v100, v100, v14, 1
	s_waitcnt lgkmcnt(0)
	v_mul_f32_e32 v93, v97, v99
	v_add_u32_e32 v99, 0x18000, v100
	v_add_u32_e32 v100, 0x1a400, v100
	v_mul_f32_e32 v101, v2, v97
	v_mul_f32_e32 v102, v2, v93
	v_cvt_pk_bf16_f32 v101, v101, v102
	ds_write_b16 v99, v101
	ds_write_b16_d16_hi v100, v101
	v_mul_f32_e32 v16, v3, v97
	v_mul_f32_e32 v17, v3, v93
	v_cvt_pk_bf16_f32 v16, v16, v17
	ds_write_b16 v99, v16 offset:144
	ds_write_b16_d16_hi v100, v16 offset:144
	v_mul_f32_e32 v101, v4, v97
	v_mul_f32_e32 v102, v4, v93
	v_cvt_pk_bf16_f32 v101, v101, v102
	ds_write_b16 v99, v101 offset:288
	ds_write_b16_d16_hi v100, v101 offset:288
	v_mul_f32_e32 v16, v5, v97
	v_mul_f32_e32 v17, v5, v93
	v_cvt_pk_bf16_f32 v16, v16, v17
	ds_write_b16 v99, v16 offset:432
	ds_write_b16_d16_hi v100, v16 offset:432
	v_mul_f32_e32 v101, v6, v97
	v_mul_f32_e32 v102, v6, v93
	v_cvt_pk_bf16_f32 v101, v101, v102
	ds_write_b16 v99, v101 offset:2304
	ds_write_b16_d16_hi v100, v101 offset:2304
	v_mul_f32_e32 v16, v7, v97
	v_mul_f32_e32 v17, v7, v93
	v_cvt_pk_bf16_f32 v16, v16, v17
	ds_write_b16 v99, v16 offset:2448
	ds_write_b16_d16_hi v100, v16 offset:2448
	v_mul_f32_e32 v101, v8, v97
	v_mul_f32_e32 v102, v8, v93
	v_cvt_pk_bf16_f32 v101, v101, v102
	ds_write_b16 v99, v101 offset:2592
	ds_write_b16_d16_hi v100, v101 offset:2592
	v_mul_f32_e32 v16, v9, v97
	v_mul_f32_e32 v17, v9, v93
	v_cvt_pk_bf16_f32 v16, v16, v17
	ds_write_b16 v99, v16 offset:2736
	ds_write_b16_d16_hi v100, v16 offset:2736
	s_and_saveexec_b64 s[28:29], vcc
	s_cbranch_execz .Lps_skip
	v_mul_u32_u24_e32 v10, 0x48, v32
	s_movk_i32 s6, 0x90
	v_add_lshl_u32 v10, v10, v14, 1
	v_mad_u32_u24 v18, v32, s6, v33
	v_add_u32_e32 v11, 0x1a400, v10
	v_add_u32_e32 v10, 0x18000, v10
	ds_write_b16 v10, v131
	ds_write_b16 v11, v131
	ds_write_b32 v18, v2
	ds_write_b16 v10, v131 offset:144
	ds_write_b16 v11, v131 offset:144
	ds_write_b32 v18, v3 offset:144
	ds_write_b16 v10, v131 offset:288
	ds_write_b16 v11, v131 offset:288
	ds_write_b32 v18, v4 offset:288
	ds_write_b16 v10, v131 offset:432
	ds_write_b16 v11, v131 offset:432
	ds_write_b32 v18, v5 offset:432
	ds_write_b16 v10, v131 offset:2304
	ds_write_b16 v11, v131 offset:2304
	ds_write_b32 v18, v6 offset:2304
	ds_write_b16 v10, v131 offset:2448
	ds_write_b16 v11, v131 offset:2448
	ds_write_b32 v18, v7 offset:2448
	ds_write_b16 v10, v131 offset:2592
	ds_write_b16 v11, v131 offset:2592
	ds_write_b32 v18, v8 offset:2592
	ds_write_b16 v10, v131 offset:2736
	ds_write_b16 v11, v131 offset:2736
	ds_write_b32 v18, v9 offset:2736
